# speed-ranked GU tail in all four steps: step 0 ranks groups by arrival at the barrier after the FFN norm, steps 1-3 by arrival after step-0 GU
# baseline (speedup 1.0000x reference)
.LBB0_800:
	s_cmp_lg_u32 s65, 0
	s_cbranch_scc1 .Lrk0_done
	s_cmp_gt_u32 s8, 7
	s_cbranch_scc1 .Lrk0_done
	s_add_u32 s98, s4, 0x302c04
	s_addc_u32 s99, s5, 0
	global_atomic_add v4, v1, v245, s[98:99] sc0
	s_lshl_b32 s100, s8, 8
	s_add_u32 s98, s4, s100
	s_addc_u32 s99, s5, 0
	s_add_u32 s98, s98, 0x302404
	s_addc_u32 s99, s99, 0
	s_waitcnt vmcnt(0)
	global_store_dword v1, v4, s[98:99]
	s_waitcnt vmcnt(0)

.LBB0_840:
	s_add_u32 s6, s6, 0xac00000
	s_addc_u32 s7, s7, 0
	v_and_b32_e32 v17, 15, v16
	v_lshrrev_b32_e32 v18, 1, v16
	s_lshl_b32 s2, s2, 5
	v_and_b32_e32 v18, 24, v18
	v_lshlrev_b32_e32 v19, 6, v17
	v_lshlrev_b32_e32 v16, 2, v16
	s_and_b32 s22, s2, 0x60
	s_add_i32 m0, s46, 0x18000
	v_lshl_add_u64 v[8:9], v[8:9], 0, s[70:71]
	v_lshl_or_b32 v19, v18, 1, v19
	v_and_b32_e32 v16, 32, v16
	v_lshl_or_b32 v144, s3, 6, v17
	s_lshl_b32 s3, s3, 13
	s_lshl_b32 s2, s22, 7
	s_waitcnt vmcnt(2)
	s_barrier
	global_load_lds_dwordx4 v[8:9], off
	v_lshl_add_u64 v[6:7], v[6:7], 0, s[70:71]
	s_add_i32 m0, s46, 0x1a000
	s_add_i32 s50, s46, 0x8000
	s_add_i32 s51, s46, 0xa000
	v_bitop3_b32 v145, s2, v19, v16 bitop3:0xf6
	global_load_lds_dwordx4 v[6:7], off
	v_lshl_add_u64 v[2:3], v[2:3], 0, s[70:71]
	s_mov_b32 m0, s50
	s_add_u32 s2, s38, 0x40080
	v_bitop3_b32 v17, v19, s3, v16 bitop3:0xde
	global_load_lds_dwordx4 v[2:3], off
	v_lshl_add_u64 v[2:3], v[4:5], 0, s[70:71]
	s_mov_b32 m0, s51
	s_addc_u32 s3, s39, 0
	global_load_lds_dwordx4 v[2:3], off
	s_add_i32 m0, s46, 0x1c000
	v_lshl_add_u64 v[2:3], s[2:3], 0, v[0:1]
	global_load_lds_dwordx4 v[2:3], off
	v_lshl_add_u64 v[2:3], s[2:3], 0, v[134:135]
	s_add_i32 m0, s46, 0x1e000
	s_cmpk_lt_u32 s9, 0x100
	global_load_lds_dwordx4 v[2:3], off
	v_lshlrev_b32_e32 v2, 14, v10
	v_and_b32_e32 v2, 0xffff8000, v2
	v_lshl_add_u32 v2, v11, 11, v2
	v_and_b32_e32 v3, 1, v10
	v_lshl_or_b32 v2, v3, 6, v2
	v_lshl_add_u32 v136, v12, 1, v2
	v_lshlrev_b32_e32 v2, 14, v13
	v_and_b32_e32 v2, 0xffff8000, v2
	s_waitcnt vmcnt(6)
	v_lshl_add_u32 v2, v14, 11, v2
	v_and_b32_e32 v3, 1, v13
	v_lshl_or_b32 v2, v3, 6, v2
	s_cselect_b64 s[14:15], -1, 0
	v_or_b32_e32 v146, s22, v18
	v_mov_b32_e32 v137, v1
	v_lshl_add_u32 v138, v15, 1, v2
	v_mov_b32_e32 v139, v1
	s_mov_b32 s52, 0
	v_add_u32_e32 v147, 0, v17
	s_barrier
	s_mov_b32 s100, 0x10000
	s_cmpk_lg_u32 s33, 0x100
	s_cbranch_scc1 .Lslot_done
	s_load_dwordx2 s[98:99], s[0:1], 0x128
	s_and_b32 s101, s8, 7
	s_lshl_b32 s101, s101, 8
	s_waitcnt lgkmcnt(0)
	s_add_u32 s98, s98, s101
	s_addc_u32 s99, s99, 0
	s_add_u32 s98, s98, 0x302400
	s_addc_u32 s99, s99, 0
	s_cmp_eq_u32 s65, 0
	s_cselect_b32 s101, 4, 0
	s_add_u32 s98, s98, s101
	s_addc_u32 s99, s99, 0
	global_load_dword v2, v1, s[98:99] sc1
	s_waitcnt vmcnt(0)
	v_readfirstlane_b32 s101, v2
	s_nop 3
	s_cmp_lt_u32 s101, 3
	s_cbranch_scc0 .Lslot_done
	s_lshl_b32 s101, s101, 5
	s_lshr_b32 s100, s8, 3
	s_add_i32 s100, s100, s101

.LBB0_843:
	s_add_i32 s52, s52, 1
	s_mul_i32 s2, s52, s34
	s_mul_hi_u32 s3, s52, s33
	s_add_i32 s3, s3, s2
	s_mul_i32 s2, s52, s33
	s_add_u32 s26, s2, s8
	s_addc_u32 s27, s3, s55
	s_cmp_lg_u32 s52, 12
	s_cbranch_scc1 .Ltail_done
	s_cmpk_lg_u32 s33, 0x100
	s_cbranch_scc1 .Ltail_done
	s_add_i32 s26, s100, 0xc00
	s_mov_b32 s27, 0
